# code placement: MFMA runs of both K-loops start on 8-byte boundaries (s_nop padding via .p2alignl)
# baseline (speedup 1.0000x reference)
.LBB0_119:
	s_add_u32 s17, s10, s24
	s_addc_u32 s31, s11, s25
	s_add_u32 s30, s17, 0x100
	s_addc_u32 s49, s31, 0
	s_and_b64 s[28:29], s[22:23], exec
	s_cselect_b32 s29, s19, s49
	s_cselect_b32 s28, s18, s30
	s_add_u32 s24, s8, s24
	s_addc_u32 s25, s9, s25
	s_add_u32 s24, s24, 0x100
	s_addc_u32 s25, s25, 0
	s_add_i32 s49, 0, 0x10000
	v_add_u32_e32 v74, s49, v77
	ds_read_b128 v[70:73], v74
	ds_read_b128 v[154:157], v74 offset:1024
	ds_read_b128 v[186:189], v74 offset:2048
	ds_read_b128 v[190:193], v74 offset:3072
	s_and_b64 s[22:23], s[22:23], exec
	s_cselect_b32 s24, s20, s24
	s_cselect_b32 s25, s21, s25
	s_add_u32 s30, s17, 0x40080
	s_addc_u32 s31, s31, 0
	s_add_i32 s52, s49, s36
	s_add_i32 m0, s37, 0xc000
	s_add_i32 s17, s37, 0xe000
	s_add_i32 s55, s52, 0x2000
	s_add_i32 s56, 0, 0x18000
	s_add_u32 s22, s28, 0x40000
	s_addc_u32 s23, s29, 0
	s_add_i32 s49, s56, s36
	s_add_i32 s57, s49, 0x2000
	ds_read_b128 v[194:197], v109
	ds_read_b128 v[198:201], v109 offset:1024
	ds_read_b128 v[202:205], v109 offset:2048
	ds_read_b128 v[206:209], v109 offset:3072
	ds_read_b128 v[210:213], v109 offset:4096
	ds_read_b128 v[214:217], v109 offset:5120
	ds_read_b128 v[218:221], v109 offset:6144
	ds_read_b128 v[222:225], v109 offset:7168
	global_load_lds_dwordx4 v64, s[30:31]
	s_mov_b32 m0, s17
	s_nop 0
	global_load_lds_dwordx4 v66, s[30:31]
	s_waitcnt vmcnt(6)
	s_waitcnt lgkmcnt(0)
	s_barrier
	s_setprio 1
	s_waitcnt lgkmcnt(0)
	.p2alignl 3, 3212836864
	v_mfma_f32_16x16x32_bf16 v[60:63], v[70:73], v[194:197], v[60:63]
	v_mfma_f32_16x16x32_bf16 v[56:59], v[186:189], v[194:197], v[56:59]
	v_mfma_f32_16x16x32_bf16 v[52:55], v[70:73], v[202:205], v[52:55]
	v_mfma_f32_16x16x32_bf16 v[48:51], v[186:189], v[202:205], v[48:51]
	v_mfma_f32_16x16x32_bf16 v[44:47], v[70:73], v[210:213], v[44:47]
	v_mfma_f32_16x16x32_bf16 v[40:43], v[186:189], v[210:213], v[40:43]
	v_mfma_f32_16x16x32_bf16 v[36:39], v[70:73], v[218:221], v[36:39]
	v_mfma_f32_16x16x32_bf16 v[32:35], v[186:189], v[218:221], v[32:35]
	v_mfma_f32_16x16x32_bf16 v[60:63], v[154:157], v[198:201], v[60:63]
	v_mfma_f32_16x16x32_bf16 v[56:59], v[190:193], v[198:201], v[56:59]
	v_mfma_f32_16x16x32_bf16 v[52:55], v[154:157], v[206:209], v[52:55]
	v_mfma_f32_16x16x32_bf16 v[48:51], v[190:193], v[206:209], v[48:51]
	v_mfma_f32_16x16x32_bf16 v[44:47], v[154:157], v[214:217], v[44:47]
	v_mfma_f32_16x16x32_bf16 v[40:43], v[190:193], v[214:217], v[40:43]
	v_mfma_f32_16x16x32_bf16 v[36:39], v[154:157], v[222:225], v[36:39]
	v_mfma_f32_16x16x32_bf16 v[32:35], v[190:193], v[222:225], v[32:35]
	s_setprio 0
	s_barrier
	s_mov_b32 m0, s52
	ds_read_b128 v[194:197], v109 offset:16384
	ds_read_b128 v[198:201], v109 offset:17408
	ds_read_b128 v[202:205], v109 offset:18432
	ds_read_b128 v[206:209], v109 offset:19456
	ds_read_b128 v[210:213], v109 offset:20480
	ds_read_b128 v[214:217], v109 offset:21504
	ds_read_b128 v[218:221], v109 offset:22528
	ds_read_b128 v[222:225], v109 offset:23552
	global_load_lds_dwordx4 v144, s[24:25]
	s_mov_b32 m0, s55
	s_nop 0
	global_load_lds_dwordx4 v68, s[24:25]
	s_mov_b32 m0, s37
	s_nop 0
	global_load_lds_dwordx4 v64, s[28:29]
	s_mov_b32 m0, s38
	s_nop 0
	global_load_lds_dwordx4 v66, s[28:29]
	s_waitcnt vmcnt(6)
	s_waitcnt lgkmcnt(0)
	s_barrier
	s_setprio 1
	s_waitcnt lgkmcnt(0)
	.p2alignl 3, 3212836864
	v_mfma_f32_16x16x32_bf16 v[28:31], v[70:73], v[194:197], v[28:31]
	v_mfma_f32_16x16x32_bf16 v[24:27], v[186:189], v[194:197], v[24:27]
	v_mfma_f32_16x16x32_bf16 v[20:23], v[70:73], v[202:205], v[20:23]
	v_mfma_f32_16x16x32_bf16 v[16:19], v[186:189], v[202:205], v[16:19]
	v_mfma_f32_16x16x32_bf16 v[12:15], v[70:73], v[210:213], v[12:15]
	v_mfma_f32_16x16x32_bf16 v[8:11], v[186:189], v[210:213], v[8:11]
	v_mfma_f32_16x16x32_bf16 v[4:7], v[70:73], v[218:221], v[4:7]
	v_mfma_f32_16x16x32_bf16 v[0:3], v[186:189], v[218:221], v[0:3]
	v_mfma_f32_16x16x32_bf16 v[28:31], v[154:157], v[198:201], v[28:31]
	v_mfma_f32_16x16x32_bf16 v[24:27], v[190:193], v[198:201], v[24:27]
	v_mfma_f32_16x16x32_bf16 v[20:23], v[154:157], v[206:209], v[20:23]
	v_mfma_f32_16x16x32_bf16 v[16:19], v[190:193], v[206:209], v[16:19]
	v_mfma_f32_16x16x32_bf16 v[12:15], v[154:157], v[214:217], v[12:15]
	v_mfma_f32_16x16x32_bf16 v[8:11], v[190:193], v[214:217], v[8:11]
	v_mfma_f32_16x16x32_bf16 v[4:7], v[154:157], v[222:225], v[4:7]
	v_mfma_f32_16x16x32_bf16 v[0:3], v[190:193], v[222:225], v[0:3]
	s_setprio 0
	s_barrier
	v_add_u32_e32 v160, s56, v77
	ds_read_b128 v[70:73], v160
	ds_read_b128 v[154:157], v160 offset:1024
	ds_read_b128 v[186:189], v160 offset:2048
	ds_read_b128 v[190:193], v160 offset:3072
	s_mov_b32 m0, s39
	ds_read_b128 v[194:197], v109 offset:32768
	ds_read_b128 v[198:201], v109 offset:33792
	ds_read_b128 v[202:205], v109 offset:34816
	ds_read_b128 v[206:209], v109 offset:35840
	ds_read_b128 v[210:213], v109 offset:36864
	ds_read_b128 v[214:217], v109 offset:37888
	ds_read_b128 v[218:221], v109 offset:38912
	ds_read_b128 v[222:225], v109 offset:39936
	global_load_lds_dwordx4 v64, s[22:23]
	s_mov_b32 m0, s40
	s_nop 0
	global_load_lds_dwordx4 v66, s[22:23]
	s_waitcnt vmcnt(6)
	s_waitcnt lgkmcnt(0)
	s_barrier
	s_setprio 1
	s_waitcnt lgkmcnt(0)
	.p2alignl 3, 3212836864
	v_mfma_f32_16x16x32_bf16 v[60:63], v[70:73], v[194:197], v[60:63]
	v_mfma_f32_16x16x32_bf16 v[56:59], v[186:189], v[194:197], v[56:59]
	v_mfma_f32_16x16x32_bf16 v[52:55], v[70:73], v[202:205], v[52:55]
	v_mfma_f32_16x16x32_bf16 v[48:51], v[186:189], v[202:205], v[48:51]
	v_mfma_f32_16x16x32_bf16 v[44:47], v[70:73], v[210:213], v[44:47]
	v_mfma_f32_16x16x32_bf16 v[40:43], v[186:189], v[210:213], v[40:43]
	v_mfma_f32_16x16x32_bf16 v[36:39], v[70:73], v[218:221], v[36:39]
	v_mfma_f32_16x16x32_bf16 v[32:35], v[186:189], v[218:221], v[32:35]
	v_mfma_f32_16x16x32_bf16 v[60:63], v[154:157], v[198:201], v[60:63]
	v_mfma_f32_16x16x32_bf16 v[56:59], v[190:193], v[198:201], v[56:59]
	v_mfma_f32_16x16x32_bf16 v[52:55], v[154:157], v[206:209], v[52:55]
	v_mfma_f32_16x16x32_bf16 v[48:51], v[190:193], v[206:209], v[48:51]
	v_mfma_f32_16x16x32_bf16 v[44:47], v[154:157], v[214:217], v[44:47]
	v_mfma_f32_16x16x32_bf16 v[40:43], v[190:193], v[214:217], v[40:43]
	v_mfma_f32_16x16x32_bf16 v[36:39], v[154:157], v[222:225], v[36:39]
	v_mfma_f32_16x16x32_bf16 v[32:35], v[190:193], v[222:225], v[32:35]
	s_setprio 0
	s_barrier
	s_add_i32 m0, s49, 0xffffff80
	ds_read_b128 v[194:197], v109 offset:49152
	ds_read_b128 v[198:201], v109 offset:50176
	ds_read_b128 v[202:205], v109 offset:51200
	ds_read_b128 v[206:209], v109 offset:52224
	ds_read_b128 v[210:213], v109 offset:53248
	ds_read_b128 v[214:217], v109 offset:54272
	ds_read_b128 v[218:221], v109 offset:55296
	ds_read_b128 v[222:225], v109 offset:56320
	global_load_lds_dwordx4 v144, s[24:25] offset:128
	s_add_i32 m0, s57, 0xffffff80
	s_nop 0
	global_load_lds_dwordx4 v68, s[24:25] offset:128
	s_add_i32 m0, s42, 0xffffff80
	s_nop 0
	global_load_lds_dwordx4 v64, s[28:29] offset:128
	s_add_i32 m0, s43, 0xffffff80
	s_nop 0
	global_load_lds_dwordx4 v66, s[28:29] offset:128
	s_waitcnt vmcnt(6)
	s_waitcnt lgkmcnt(0)
	s_barrier
	s_setprio 1
	s_waitcnt lgkmcnt(0)
	.p2alignl 3, 3212836864
	v_mfma_f32_16x16x32_bf16 v[28:31], v[70:73], v[194:197], v[28:31]
	v_mfma_f32_16x16x32_bf16 v[24:27], v[186:189], v[194:197], v[24:27]
	v_mfma_f32_16x16x32_bf16 v[20:23], v[70:73], v[202:205], v[20:23]
	v_mfma_f32_16x16x32_bf16 v[16:19], v[186:189], v[202:205], v[16:19]
	v_mfma_f32_16x16x32_bf16 v[12:15], v[70:73], v[210:213], v[12:15]
	v_mfma_f32_16x16x32_bf16 v[8:11], v[186:189], v[210:213], v[8:11]
	v_mfma_f32_16x16x32_bf16 v[4:7], v[70:73], v[218:221], v[4:7]
	v_mfma_f32_16x16x32_bf16 v[0:3], v[186:189], v[218:221], v[0:3]
	v_mfma_f32_16x16x32_bf16 v[28:31], v[154:157], v[198:201], v[28:31]
	v_mfma_f32_16x16x32_bf16 v[24:27], v[190:193], v[198:201], v[24:27]
	v_mfma_f32_16x16x32_bf16 v[20:23], v[154:157], v[206:209], v[20:23]
	v_mfma_f32_16x16x32_bf16 v[16:19], v[190:193], v[206:209], v[16:19]
	v_mfma_f32_16x16x32_bf16 v[12:15], v[154:157], v[214:217], v[12:15]
	v_mfma_f32_16x16x32_bf16 v[8:11], v[190:193], v[214:217], v[8:11]
	v_mfma_f32_16x16x32_bf16 v[4:7], v[154:157], v[222:225], v[4:7]
	v_mfma_f32_16x16x32_bf16 v[0:3], v[190:193], v[222:225], v[0:3]
	s_setprio 0
	s_barrier
	s_andn2_b64 vcc, exec, s[12:13]
	s_mov_b64 s[22:23], -1
	s_mov_b64 s[12:13], 0
	s_mov_b64 s[24:25], 0x100
	s_cbranch_vccz .LBB0_119
	s_and_b64 vcc, exec, s[14:15]
	s_cbranch_vccz .LBB0_122
	s_barrier

.LBB0_246:
	s_add_i32 s90, s42, 2
	s_add_u32 s91, s6, 0x80
	s_addc_u32 s43, s7, 0
	s_cmp_eq_u32 s72, s42
	s_cselect_b32 s43, s89, s43
	s_cselect_b32 s42, s88, s91
	s_cselect_b32 s93, s1, s66
	s_cselect_b32 s92, s0, s8
	ds_read_b128 v[128:131], v222
	ds_read_b128 v[132:135], v222 offset:1024
	ds_read_b128 v[136:139], v222 offset:2048
	ds_read_b128 v[140:143], v222 offset:3072
	ds_read_b128 v[168:171], v222 offset:16384
	ds_read_b128 v[172:175], v222 offset:17408
	ds_read_b128 v[176:179], v222 offset:18432
	ds_read_b128 v[180:183], v222 offset:19456
	s_add_i32 m0, s68, 0xc000
	ds_read_b128 v[190:193], v188
	ds_read_b128 v[194:197], v188 offset:1024
	ds_read_b128 v[198:201], v188 offset:2048
	ds_read_b128 v[202:205], v188 offset:3072
	ds_read_b128 v[206:209], v188 offset:4096
	ds_read_b128 v[210:213], v188 offset:5120
	ds_read_b128 v[214:217], v188 offset:6144
	ds_read_b128 v[218:221], v188 offset:7168
	global_load_lds_dwordx4 v162, s[6:7]
	s_add_i32 m0, s68, 0xe000
	s_nop 0
	global_load_lds_dwordx4 v164, s[6:7]
	s_waitcnt vmcnt(8)
	s_waitcnt lgkmcnt(0)
	s_barrier
	s_setprio 1
	s_waitcnt lgkmcnt(0)
	.p2alignl 3, 3212836864
	v_mfma_f32_16x16x32_bf16 v[124:127], v[128:131], v[190:193], v[124:127]
	v_mfma_f32_16x16x32_bf16 v[120:123], v[136:139], v[190:193], v[120:123]
	v_mfma_f32_16x16x32_bf16 v[116:119], v[128:131], v[198:201], v[116:119]
	v_mfma_f32_16x16x32_bf16 v[112:115], v[136:139], v[198:201], v[112:115]
	v_mfma_f32_16x16x32_bf16 v[100:103], v[128:131], v[206:209], v[100:103]
	v_mfma_f32_16x16x32_bf16 v[96:99], v[136:139], v[206:209], v[96:99]
	v_mfma_f32_16x16x32_bf16 v[84:87], v[128:131], v[214:217], v[84:87]
	v_mfma_f32_16x16x32_bf16 v[80:83], v[136:139], v[214:217], v[80:83]
	v_mfma_f32_16x16x32_bf16 v[124:127], v[132:135], v[194:197], v[124:127]
	v_mfma_f32_16x16x32_bf16 v[120:123], v[140:143], v[194:197], v[120:123]
	v_mfma_f32_16x16x32_bf16 v[116:119], v[132:135], v[202:205], v[116:119]
	v_mfma_f32_16x16x32_bf16 v[112:115], v[140:143], v[202:205], v[112:115]
	v_mfma_f32_16x16x32_bf16 v[100:103], v[132:135], v[210:213], v[100:103]
	v_mfma_f32_16x16x32_bf16 v[96:99], v[140:143], v[210:213], v[96:99]
	v_mfma_f32_16x16x32_bf16 v[84:87], v[132:135], v[218:221], v[84:87]
	v_mfma_f32_16x16x32_bf16 v[80:83], v[140:143], v[218:221], v[80:83]
	s_setprio 0
	s_setprio 1
	v_mfma_f32_16x16x32_bf16 v[108:111], v[168:171], v[190:193], v[108:111]
	v_mfma_f32_16x16x32_bf16 v[104:107], v[176:179], v[190:193], v[104:107]
	v_mfma_f32_16x16x32_bf16 v[92:95], v[168:171], v[198:201], v[92:95]
	v_mfma_f32_16x16x32_bf16 v[88:91], v[176:179], v[198:201], v[88:91]
	v_mfma_f32_16x16x32_bf16 v[76:79], v[168:171], v[206:209], v[76:79]
	v_mfma_f32_16x16x32_bf16 v[72:75], v[176:179], v[206:209], v[72:75]
	v_mfma_f32_16x16x32_bf16 v[68:71], v[168:171], v[214:217], v[68:71]
	v_mfma_f32_16x16x32_bf16 v[64:67], v[176:179], v[214:217], v[64:67]
	v_mfma_f32_16x16x32_bf16 v[108:111], v[172:175], v[194:197], v[108:111]
	v_mfma_f32_16x16x32_bf16 v[104:107], v[180:183], v[194:197], v[104:107]
	v_mfma_f32_16x16x32_bf16 v[92:95], v[172:175], v[202:205], v[92:95]
	v_mfma_f32_16x16x32_bf16 v[88:91], v[180:183], v[202:205], v[88:91]
	v_mfma_f32_16x16x32_bf16 v[76:79], v[172:175], v[210:213], v[76:79]
	v_mfma_f32_16x16x32_bf16 v[72:75], v[180:183], v[210:213], v[72:75]
	v_mfma_f32_16x16x32_bf16 v[68:71], v[172:175], v[218:221], v[68:71]
	v_mfma_f32_16x16x32_bf16 v[64:67], v[180:183], v[218:221], v[64:67]
	s_setprio 0
	s_barrier
	s_add_i32 m0, s15, 0x10000
	ds_read_b128 v[190:193], v188 offset:16384
	ds_read_b128 v[194:197], v188 offset:17408
	ds_read_b128 v[198:201], v188 offset:18432
	ds_read_b128 v[202:205], v188 offset:19456
	ds_read_b128 v[206:209], v188 offset:20480
	ds_read_b128 v[210:213], v188 offset:21504
	ds_read_b128 v[214:217], v188 offset:22528
	ds_read_b128 v[218:221], v188 offset:23552
	global_load_lds_dwordx4 v148, s[92:93]
	s_add_i32 m0, s15, 0x12000
	s_nop 0
	global_load_lds_dwordx4 v152, s[92:93]
	s_add_i32 m0, s15, 0x14000
	s_add_u32 s92, s92, s21
	s_addc_u32 s93, s93, 0
	global_load_lds_dwordx4 v148, s[92:93]
	s_add_i32 m0, s15, 0x16000
	s_nop 0
	global_load_lds_dwordx4 v152, s[92:93]
	s_mov_b32 m0, s68
	s_nop 0
	global_load_lds_dwordx4 v146, s[42:43]
	s_mov_b32 m0, s23
	s_nop 0
	global_load_lds_dwordx4 v150, s[42:43]
	s_waitcnt vmcnt(8)
	s_waitcnt lgkmcnt(0)
	s_barrier
	s_setprio 1
	s_waitcnt lgkmcnt(0)
	.p2alignl 3, 3212836864
	v_mfma_f32_16x16x32_bf16 v[60:63], v[128:131], v[190:193], v[60:63]
	v_mfma_f32_16x16x32_bf16 v[56:59], v[136:139], v[190:193], v[56:59]
	v_mfma_f32_16x16x32_bf16 v[52:55], v[128:131], v[198:201], v[52:55]
	v_mfma_f32_16x16x32_bf16 v[48:51], v[136:139], v[198:201], v[48:51]
	v_mfma_f32_16x16x32_bf16 v[36:39], v[128:131], v[206:209], v[36:39]
	v_mfma_f32_16x16x32_bf16 v[32:35], v[136:139], v[206:209], v[32:35]
	v_mfma_f32_16x16x32_bf16 v[20:23], v[128:131], v[214:217], v[20:23]
	v_mfma_f32_16x16x32_bf16 v[16:19], v[136:139], v[214:217], v[16:19]
	v_mfma_f32_16x16x32_bf16 v[60:63], v[132:135], v[194:197], v[60:63]
	v_mfma_f32_16x16x32_bf16 v[56:59], v[140:143], v[194:197], v[56:59]
	v_mfma_f32_16x16x32_bf16 v[52:55], v[132:135], v[202:205], v[52:55]
	v_mfma_f32_16x16x32_bf16 v[48:51], v[140:143], v[202:205], v[48:51]
	v_mfma_f32_16x16x32_bf16 v[36:39], v[132:135], v[210:213], v[36:39]
	v_mfma_f32_16x16x32_bf16 v[32:35], v[140:143], v[210:213], v[32:35]
	v_mfma_f32_16x16x32_bf16 v[20:23], v[132:135], v[218:221], v[20:23]
	v_mfma_f32_16x16x32_bf16 v[16:19], v[140:143], v[218:221], v[16:19]
	s_setprio 0
	s_setprio 1
	v_mfma_f32_16x16x32_bf16 v[44:47], v[168:171], v[190:193], v[44:47]
	v_mfma_f32_16x16x32_bf16 v[40:43], v[176:179], v[190:193], v[40:43]
	v_mfma_f32_16x16x32_bf16 v[28:31], v[168:171], v[198:201], v[28:31]
	v_mfma_f32_16x16x32_bf16 v[24:27], v[176:179], v[198:201], v[24:27]
	v_mfma_f32_16x16x32_bf16 v[12:15], v[168:171], v[206:209], v[12:15]
	v_mfma_f32_16x16x32_bf16 v[8:11], v[176:179], v[206:209], v[8:11]
	v_mfma_f32_16x16x32_bf16 v[4:7], v[168:171], v[214:217], v[4:7]
	v_mfma_f32_16x16x32_bf16 v[0:3], v[176:179], v[214:217], v[0:3]
	v_mfma_f32_16x16x32_bf16 v[44:47], v[172:175], v[194:197], v[44:47]
	v_mfma_f32_16x16x32_bf16 v[40:43], v[180:183], v[194:197], v[40:43]
	v_mfma_f32_16x16x32_bf16 v[28:31], v[172:175], v[202:205], v[28:31]
	v_mfma_f32_16x16x32_bf16 v[24:27], v[180:183], v[202:205], v[24:27]
	v_mfma_f32_16x16x32_bf16 v[12:15], v[172:175], v[210:213], v[12:15]
	v_mfma_f32_16x16x32_bf16 v[8:11], v[180:183], v[210:213], v[8:11]
	v_mfma_f32_16x16x32_bf16 v[4:7], v[172:175], v[218:221], v[4:7]
	v_mfma_f32_16x16x32_bf16 v[0:3], v[180:183], v[218:221], v[0:3]
	s_setprio 0
	s_barrier
	ds_read_b128 v[128:131], v222 offset:32768
	ds_read_b128 v[132:135], v222 offset:33792
	ds_read_b128 v[136:139], v222 offset:34816
	ds_read_b128 v[140:143], v222 offset:35840
	ds_read_b128 v[168:171], v222 offset:49152
	ds_read_b128 v[172:175], v222 offset:50176
	ds_read_b128 v[176:179], v222 offset:51200
	ds_read_b128 v[180:183], v222 offset:52224
	s_add_u32 s42, s42, s48
	s_addc_u32 s43, s43, 0
	s_mov_b32 m0, s40
	ds_read_b128 v[190:193], v188 offset:32768
	ds_read_b128 v[194:197], v188 offset:33792
	ds_read_b128 v[198:201], v188 offset:34816
	ds_read_b128 v[202:205], v188 offset:35840
	ds_read_b128 v[206:209], v188 offset:36864
	ds_read_b128 v[210:213], v188 offset:37888
	ds_read_b128 v[214:217], v188 offset:38912
	ds_read_b128 v[218:221], v188 offset:39936
	global_load_lds_dwordx4 v146, s[42:43]
	s_mov_b32 m0, s41
	s_nop 0
	global_load_lds_dwordx4 v150, s[42:43]
	s_waitcnt vmcnt(8)
	s_waitcnt lgkmcnt(0)
	s_barrier
	s_setprio 1
	s_waitcnt lgkmcnt(0)
	.p2alignl 3, 3212836864
	v_mfma_f32_16x16x32_bf16 v[124:127], v[128:131], v[190:193], v[124:127]
	v_mfma_f32_16x16x32_bf16 v[120:123], v[136:139], v[190:193], v[120:123]
	v_mfma_f32_16x16x32_bf16 v[116:119], v[128:131], v[198:201], v[116:119]
	v_mfma_f32_16x16x32_bf16 v[112:115], v[136:139], v[198:201], v[112:115]
	v_mfma_f32_16x16x32_bf16 v[100:103], v[128:131], v[206:209], v[100:103]
	v_mfma_f32_16x16x32_bf16 v[96:99], v[136:139], v[206:209], v[96:99]
	v_mfma_f32_16x16x32_bf16 v[84:87], v[128:131], v[214:217], v[84:87]
	v_mfma_f32_16x16x32_bf16 v[80:83], v[136:139], v[214:217], v[80:83]
	v_mfma_f32_16x16x32_bf16 v[124:127], v[132:135], v[194:197], v[124:127]
	v_mfma_f32_16x16x32_bf16 v[120:123], v[140:143], v[194:197], v[120:123]
	v_mfma_f32_16x16x32_bf16 v[116:119], v[132:135], v[202:205], v[116:119]
	v_mfma_f32_16x16x32_bf16 v[112:115], v[140:143], v[202:205], v[112:115]
	v_mfma_f32_16x16x32_bf16 v[100:103], v[132:135], v[210:213], v[100:103]
	v_mfma_f32_16x16x32_bf16 v[96:99], v[140:143], v[210:213], v[96:99]
	v_mfma_f32_16x16x32_bf16 v[84:87], v[132:135], v[218:221], v[84:87]
	v_mfma_f32_16x16x32_bf16 v[80:83], v[140:143], v[218:221], v[80:83]
	s_setprio 0
	s_setprio 1
	v_mfma_f32_16x16x32_bf16 v[108:111], v[168:171], v[190:193], v[108:111]
	v_mfma_f32_16x16x32_bf16 v[104:107], v[176:179], v[190:193], v[104:107]
	v_mfma_f32_16x16x32_bf16 v[92:95], v[168:171], v[198:201], v[92:95]
	v_mfma_f32_16x16x32_bf16 v[88:91], v[176:179], v[198:201], v[88:91]
	v_mfma_f32_16x16x32_bf16 v[76:79], v[168:171], v[206:209], v[76:79]
	v_mfma_f32_16x16x32_bf16 v[72:75], v[176:179], v[206:209], v[72:75]
	v_mfma_f32_16x16x32_bf16 v[68:71], v[168:171], v[214:217], v[68:71]
	v_mfma_f32_16x16x32_bf16 v[64:67], v[176:179], v[214:217], v[64:67]
	v_mfma_f32_16x16x32_bf16 v[108:111], v[172:175], v[194:197], v[108:111]
	v_mfma_f32_16x16x32_bf16 v[104:107], v[180:183], v[194:197], v[104:107]
	v_mfma_f32_16x16x32_bf16 v[92:95], v[172:175], v[202:205], v[92:95]
	v_mfma_f32_16x16x32_bf16 v[88:91], v[180:183], v[202:205], v[88:91]
	v_mfma_f32_16x16x32_bf16 v[76:79], v[172:175], v[210:213], v[76:79]
	v_mfma_f32_16x16x32_bf16 v[72:75], v[180:183], v[210:213], v[72:75]
	v_mfma_f32_16x16x32_bf16 v[68:71], v[172:175], v[218:221], v[68:71]
	v_mfma_f32_16x16x32_bf16 v[64:67], v[180:183], v[218:221], v[64:67]
	s_setprio 0
	s_barrier
	s_sub_u32 s92, s92, s21
	s_subb_u32 s93, s93, 0
	s_add_i32 m0, s15, 0x17f80
	ds_read_b128 v[190:193], v188 offset:49152
	ds_read_b128 v[194:197], v188 offset:50176
	ds_read_b128 v[198:201], v188 offset:51200
	ds_read_b128 v[202:205], v188 offset:52224
	ds_read_b128 v[206:209], v188 offset:53248
	ds_read_b128 v[210:213], v188 offset:54272
	ds_read_b128 v[214:217], v188 offset:55296
	ds_read_b128 v[218:221], v188 offset:56320
	global_load_lds_dwordx4 v148, s[92:93] offset:128
	s_add_i32 m0, s15, 0x19f80
	s_nop 0
	global_load_lds_dwordx4 v152, s[92:93] offset:128
	s_add_u32 s92, s92, s21
	s_addc_u32 s93, s93, 0
	s_add_i32 m0, s15, 0x1bf80
	s_add_u32 s6, s6, 0x100
	s_addc_u32 s7, s7, 0
	global_load_lds_dwordx4 v148, s[92:93] offset:128
	s_add_i32 m0, s15, 0x1df80
	s_sub_u32 s42, s42, s48
	s_subb_u32 s43, s43, 0
	global_load_lds_dwordx4 v152, s[92:93] offset:128
	s_add_i32 m0, s64, 0xffffff80
	s_add_u32 s8, s8, 0x100
	s_addc_u32 s66, s66, 0
	global_load_lds_dwordx4 v146, s[42:43] offset:128
	s_add_i32 m0, s65, 0xffffff80
	s_nop 0
	global_load_lds_dwordx4 v150, s[42:43] offset:128
	s_waitcnt vmcnt(8)
	s_waitcnt lgkmcnt(0)
	s_barrier
	s_setprio 1
	s_waitcnt lgkmcnt(0)
	.p2alignl 3, 3212836864
	v_mfma_f32_16x16x32_bf16 v[60:63], v[128:131], v[190:193], v[60:63]
	v_mfma_f32_16x16x32_bf16 v[56:59], v[136:139], v[190:193], v[56:59]
	v_mfma_f32_16x16x32_bf16 v[52:55], v[128:131], v[198:201], v[52:55]
	v_mfma_f32_16x16x32_bf16 v[48:51], v[136:139], v[198:201], v[48:51]
	v_mfma_f32_16x16x32_bf16 v[36:39], v[128:131], v[206:209], v[36:39]
	v_mfma_f32_16x16x32_bf16 v[32:35], v[136:139], v[206:209], v[32:35]
	v_mfma_f32_16x16x32_bf16 v[20:23], v[128:131], v[214:217], v[20:23]
	v_mfma_f32_16x16x32_bf16 v[16:19], v[136:139], v[214:217], v[16:19]
	v_mfma_f32_16x16x32_bf16 v[60:63], v[132:135], v[194:197], v[60:63]
	v_mfma_f32_16x16x32_bf16 v[56:59], v[140:143], v[194:197], v[56:59]
	v_mfma_f32_16x16x32_bf16 v[52:55], v[132:135], v[202:205], v[52:55]
	v_mfma_f32_16x16x32_bf16 v[48:51], v[140:143], v[202:205], v[48:51]
	v_mfma_f32_16x16x32_bf16 v[36:39], v[132:135], v[210:213], v[36:39]
	v_mfma_f32_16x16x32_bf16 v[32:35], v[140:143], v[210:213], v[32:35]
	v_mfma_f32_16x16x32_bf16 v[20:23], v[132:135], v[218:221], v[20:23]
	v_mfma_f32_16x16x32_bf16 v[16:19], v[140:143], v[218:221], v[16:19]
	s_setprio 0
	s_setprio 1
	v_mfma_f32_16x16x32_bf16 v[44:47], v[168:171], v[190:193], v[44:47]
	v_mfma_f32_16x16x32_bf16 v[40:43], v[176:179], v[190:193], v[40:43]
	v_mfma_f32_16x16x32_bf16 v[28:31], v[168:171], v[198:201], v[28:31]
	v_mfma_f32_16x16x32_bf16 v[24:27], v[176:179], v[198:201], v[24:27]
	v_mfma_f32_16x16x32_bf16 v[12:15], v[168:171], v[206:209], v[12:15]
	v_mfma_f32_16x16x32_bf16 v[8:11], v[176:179], v[206:209], v[8:11]
	v_mfma_f32_16x16x32_bf16 v[4:7], v[168:171], v[214:217], v[4:7]
	v_mfma_f32_16x16x32_bf16 v[0:3], v[176:179], v[214:217], v[0:3]
	v_mfma_f32_16x16x32_bf16 v[44:47], v[172:175], v[194:197], v[44:47]
	v_mfma_f32_16x16x32_bf16 v[40:43], v[180:183], v[194:197], v[40:43]
	v_mfma_f32_16x16x32_bf16 v[28:31], v[172:175], v[202:205], v[28:31]
	v_mfma_f32_16x16x32_bf16 v[24:27], v[180:183], v[202:205], v[24:27]
	v_mfma_f32_16x16x32_bf16 v[12:15], v[172:175], v[210:213], v[12:15]
	v_mfma_f32_16x16x32_bf16 v[8:11], v[180:183], v[210:213], v[8:11]
	v_mfma_f32_16x16x32_bf16 v[4:7], v[172:175], v[218:221], v[4:7]
	v_mfma_f32_16x16x32_bf16 v[0:3], v[180:183], v[218:221], v[0:3]
	s_setprio 0
	s_barrier
	s_cmp_ge_u32 s90, s55
	s_mov_b32 s42, s90
	s_cbranch_scc0 .LBB0_246
	s_and_b64 vcc, exec, s[86:87]
	s_cbranch_vccz .LBB0_249
	s_barrier
